# partner P halves requested behind the first score MFMA (needed only by the third block-0 P.V MFMA)
# baseline (speedup 1.0000x reference)
; #define SBAR() __builtin_amdgcn_sched_barrier(0)
; #define KDMA(k0, b) do { const char* g_ = (const char*)(Kh + (long)(k0) * DM); char* l_ = K_lds + (b) * 16384 + wu * 1024; \
;     DMA16(g_ + koff[0], l_); DMA16(g_ + koff[1], l_ + 8192); } while (0)
; #define VDMA(k0, b) do { const char* g_ = (const char*)(Vh + (long)(k0) * DM); char* l_ = V_lds + (b) * 32768 + wu * 1024; \
;     DMA16(g_ + voff[0], l_); DMA16(g_ + voff[1], l_ + 8192); DMA16(g_ + voff[0] + 256, l_ + 16384); DMA16(g_ + voff[1] + 256, l_ + 16384 + 8192); } while (0)
; #define VRD(D0, X) do { X##0 = tr_read<v_rd_off(D0, 0, 0)>(vb); X##1 = tr_read<v_rd_off(D0, 0, 1)>(vb); X##2 = tr_read<v_rd_off(D0, 1, 0)>(vb); X##3 = tr_read<v_rd_off(D0, 1, 1)>(vb); \
;     X##4 = tr_read<v_rd_off(D0, 2, 0)>(vb); X##5 = tr_read<v_rd_off(D0, 2, 1)>(vb); X##6 = tr_read<v_rd_off(D0, 3, 0)>(vb); X##7 = tr_read<v_rd_off(D0, 3, 1)>(vb); } while (0)
; template <int PROBE, int MODE>
; DI void dattn_body(const u16* __restrict__ Qb, const u16* __restrict__ Kh, const u16* __restrict__ Vh, u16* __restrict__ Ob, const u16* __restrict__ O1, float lam, const float* __restrict__ subg, int seq, int q0, float kmax2, char* lds) {
;     ...
;       if (j + 2 < NT) KDMA((j + 2) * KVBLK, j & 1);
;       if (more) VDMA((j + 1) * KVBLK, (j + 1) & 1);
;     }
;     bf16x8 kf[8];
;     if (more) { const char* Ks_ = K_lds + ((j + 1) & 1) * 16384;
; #pragma unroll
;       for (int d0 = 0; d0 < 8; ++d0) kf[d0] = *reinterpret_cast<const bf16x8*>(Ks_ + KSWZ(32 * kh + r32, (d0 * 16 + hi * 8) * 2)); }
;     const bf16x8 pb0 = *(const bf16x8*)(pr + (j & 1) * 16384), pb1 = *(const bf16x8*)(pr + (j & 1) * 16384 + 16);
;     const int vb = vb0 + (j & 1) * 32768;
;     s16x4 va0, va1, va2, va3, va4, va5, va6, va7, vc0, vc1, vc2, vc3, vc4, vc5, vc6, vc7;
;     VRD(0, va);
;     if (more) { asm volatile("s_waitcnt lgkmcnt(10)" ::: "memory"); SBAR();
;       if (!(PROBE & 4)) { S = f32x16{};
; #pragma unroll
;       for (int d0 = 0; d0 < 8; ++d0) S = __builtin_amdgcn_mfma_f32_32x32x16_bf16(kf[d0], qr[d0], S, 0, 0, 0); }
;       SBAR(); }
;     const bf16x8 A0 = kh ? pb0 : po0, A1 = kh ? pb1 : po1, A2 = kh ? po0 : pb0, A3 = kh ? po1 : pb1;
;     SMX_SETUP(j + 1)
;     ...
;     LWAIT(); VRD(1, vc); VMMP(0, va); SMXP(0);
;     LWAIT(); VRD(2, va); VMMP(1, vc); SMXP(1);
;     LWAIT(); VRD(3, vc); VMMP(2, va); SMXP(2);
;     LWAIT(); VMMP(3, vc); SMXP(3);
.Lfast0:
	s_sub_i32 s72, s18, 64
	s_and_b32 s101, s25, 0x4000
	s_addk_i32 s25, 0x4000
	s_and_b32 s19, s25, 0x4000
	s_and_b32 s48, s55, 1
	v_lshl_add_u32 v162, s48, 14, v210
	s_bfe_u32 s100, s85, 0x1000a
	s_lshl_b32 s100, s100, 13
	s_lshl_b32 s48, s48, 15
	s_sub_i32 s74, s48, s100
	s_add_i32 s48, s48, s100
	v_add_u32_e32 v216, s48, v212
	v_add_u32_e32 v233, s74, v212
	v_add_u32_e32 v68, s19, v213
	v_add_u32_e32 v64, v68, v198
	v_add_u32_e32 v69, v68, v199
	ds_read_b64_tr_b16 v[234:235], v216 offset:0
	ds_read_b64_tr_b16 v[236:237], v216 offset:0x800
	ds_read_b128 v[64:67], v64
	ds_read_b128 v[118:121], v69
	v_add_u32_e32 v69, v68, v200
	v_add_u32_e32 v70, v68, v201
	ds_read_b128 v[122:125], v69
	ds_read_b128 v[126:129], v70
	ds_read_b64_tr_b16 v[238:239], v216 offset:0x1000
	ds_read_b64_tr_b16 v[240:241], v216 offset:0x1800
	v_add_u32_e32 v69, v68, v202
	v_add_u32_e32 v70, v68, v203
	ds_read_b128 v[134:137], v69
	ds_read_b128 v[138:141], v70
	v_add_u32_e32 v142, v68, v204
	v_add_u32_e32 v146, v68, v205
	s_cmp_gt_i32 s72, s87
	s_cselect_b32 s100, s21, s20
	v_sub_f32_e32 v160, s100, v158
	s_lshl_b32 s48, s72, 12
	s_add_u32 s48, s16, s48
	s_addc_u32 s49, s17, 0
	s_add_u32 s74, s48, 0x100
	s_addc_u32 s75, s49, 0
	s_and_b32 s100, s54, 0x8000
	s_add_i32 s100, s85, s100
	s_waitcnt lgkmcnt(8)
	v_mfma_f32_32x32x16_bf16 v[0:15], v[114:117], v[234:237], v[0:15]
	ds_read_b64_tr_b16 v[242:243], v233 offset:0x2000
	ds_read_b64_tr_b16 v[244:245], v233 offset:0x2800
	s_waitcnt lgkmcnt(9)
	v_mfma_f32_32x32x16_bf16 v[64:79], v[64:67], v[82:85], 0
	ds_read_b128 v[166:169], v162 offset:16
	ds_read_b128 v[162:165], v162
	s_waitcnt lgkmcnt(10)
	v_mfma_f32_32x32x16_bf16 v[64:79], v[118:121], v[86:89], v[64:79]
	ds_read_b128 v[142:145], v142
	ds_read_b128 v[146:149], v146
	s_waitcnt lgkmcnt(11)
	v_mfma_f32_32x32x16_bf16 v[64:79], v[122:125], v[90:93], v[64:79]
	ds_read_b64_tr_b16 v[246:247], v233 offset:0x3000
	ds_read_b64_tr_b16 v[248:249], v233 offset:0x3800
	s_waitcnt lgkmcnt(12)
	v_mfma_f32_32x32x16_bf16 v[64:79], v[126:129], v[94:97], v[64:79]
	ds_read_b64_tr_b16 v[126:127], v233 offset:0x3200
	ds_read_b64_tr_b16 v[128:129], v233 offset:0x3a00
	s_waitcnt lgkmcnt(12)
	v_mfma_f32_32x32x16_bf16 v[0:15], v[130:133], v[238:241], v[0:15]
	s_mov_b32 m0, s100
	s_waitcnt lgkmcnt(11)
	v_mfma_f32_32x32x16_bf16 v[64:79], v[134:137], v[98:101], v[64:79]
	global_load_lds_dwordx4 v176, s[48:49]
	ds_read_b64_tr_b16 v[134:135], v233 offset:0x2200
	ds_read_b64_tr_b16 v[136:137], v233 offset:0x2a00
	s_add_i32 m0, s100, 0x2000
	s_waitcnt lgkmcnt(12)
	v_mfma_f32_32x32x16_bf16 v[64:79], v[138:141], v[102:105], v[64:79]
	global_load_lds_dwordx4 v156, s[48:49]
	ds_read_b64_tr_b16 v[138:139], v216 offset:0x200
	ds_read_b64_tr_b16 v[140:141], v216 offset:0xa00
	s_add_i32 m0, s100, 0x4000
	s_waitcnt lgkmcnt(10)
	v_mfma_f32_32x32x16_bf16 v[0:15], v[162:165], v[242:245], v[0:15]
	global_load_lds_dwordx4 v176, s[74:75]
	s_add_i32 m0, s100, 0x6000
	s_waitcnt lgkmcnt(9)
	v_mfma_f32_32x32x16_bf16 v[64:79], v[142:145], v[106:109], v[64:79]
	ds_read_b64_tr_b16 v[142:143], v216 offset:0x1200
	ds_read_b64_tr_b16 v[144:145], v216 offset:0x1a00
	s_waitcnt lgkmcnt(10)
	v_mfma_f32_32x32x16_bf16 v[64:79], v[146:149], v[110:113], v[64:79]
	global_load_lds_dwordx4 v156, s[74:75]
	s_waitcnt lgkmcnt(8)
	v_mfma_f32_32x32x16_bf16 v[0:15], v[166:169], v[246:249], v[0:15]
	s_add_i32 s48, s55, 2
	s_cmp_ge_u32 s48, s11
	s_cbranch_scc1 .Lfast0_k_done
	s_lshl_b32 s48, s18, 12
	s_add_u32 s48, s14, s48
	s_addc_u32 s49, s15, 0
	s_add_i32 s100, s82, s101
	s_mov_b32 m0, s100
	s_nop 0
	global_load_lds_dwordx4 v152, s[48:49]
	s_add_i32 m0, s100, 0x2000
	s_nop 0
	global_load_lds_dwordx4 v154, s[48:49]

; #define SBAR() __builtin_amdgcn_sched_barrier(0)
; #define KDMA(k0, b) do { const char* g_ = (const char*)(Kh + (long)(k0) * DM); char* l_ = K_lds + (b) * 16384 + wu * 1024; \
;     DMA16(g_ + koff[0], l_); DMA16(g_ + koff[1], l_ + 8192); } while (0)
; #define VDMA(k0, b) do { const char* g_ = (const char*)(Vh + (long)(k0) * DM); char* l_ = V_lds + (b) * 32768 + wu * 1024; \
;     DMA16(g_ + voff[0], l_); DMA16(g_ + voff[1], l_ + 8192); DMA16(g_ + voff[0] + 256, l_ + 16384); DMA16(g_ + voff[1] + 256, l_ + 16384 + 8192); } while (0)
; #define VRD(D0, X) do { X##0 = tr_read<v_rd_off(D0, 0, 0)>(vb); X##1 = tr_read<v_rd_off(D0, 0, 1)>(vb); X##2 = tr_read<v_rd_off(D0, 1, 0)>(vb); X##3 = tr_read<v_rd_off(D0, 1, 1)>(vb); \
;     X##4 = tr_read<v_rd_off(D0, 2, 0)>(vb); X##5 = tr_read<v_rd_off(D0, 2, 1)>(vb); X##6 = tr_read<v_rd_off(D0, 3, 0)>(vb); X##7 = tr_read<v_rd_off(D0, 3, 1)>(vb); } while (0)
; template <int PROBE, int MODE>
; DI void dattn_body(const u16* __restrict__ Qb, const u16* __restrict__ Kh, const u16* __restrict__ Vh, u16* __restrict__ Ob, const u16* __restrict__ O1, float lam, const float* __restrict__ subg, int seq, int q0, float kmax2, char* lds) {
;     ...
;       if (j + 2 < NT) KDMA((j + 2) * KVBLK, j & 1);
;       if (more) VDMA((j + 1) * KVBLK, (j + 1) & 1);
;     }
;     bf16x8 kf[8];
;     if (more) { const char* Ks_ = K_lds + ((j + 1) & 1) * 16384;
; #pragma unroll
;       for (int d0 = 0; d0 < 8; ++d0) kf[d0] = *reinterpret_cast<const bf16x8*>(Ks_ + KSWZ(32 * kh + r32, (d0 * 16 + hi * 8) * 2)); }
;     const bf16x8 pb0 = *(const bf16x8*)(pr + (j & 1) * 16384), pb1 = *(const bf16x8*)(pr + (j & 1) * 16384 + 16);
;     const int vb = vb0 + (j & 1) * 32768;
;     s16x4 va0, va1, va2, va3, va4, va5, va6, va7, vc0, vc1, vc2, vc3, vc4, vc5, vc6, vc7;
;     VRD(0, va);
;     if (more) { asm volatile("s_waitcnt lgkmcnt(10)" ::: "memory"); SBAR();
;       if (!(PROBE & 4)) { S = f32x16{};
; #pragma unroll
;       for (int d0 = 0; d0 < 8; ++d0) S = __builtin_amdgcn_mfma_f32_32x32x16_bf16(kf[d0], qr[d0], S, 0, 0, 0); }
;       SBAR(); }
;     const bf16x8 A0 = kh ? pb0 : po0, A1 = kh ? pb1 : po1, A2 = kh ? po0 : pb0, A3 = kh ? po1 : pb1;
;     SMX_SETUP(j + 1)
;     ...
;     LWAIT(); VRD(1, vc); VMMP(0, va); SMXP(0);
;     LWAIT(); VRD(2, va); VMMP(1, vc); SMXP(1);
;     LWAIT(); VRD(3, vc); VMMP(2, va); SMXP(2);
;     LWAIT(); VMMP(3, vc); SMXP(3);
.Lfast1:
	s_sub_i32 s72, s0, 64
	s_and_b32 s101, s24, 0x4000
	s_addk_i32 s24, 0x4000
	s_and_b32 s1, s24, 0x4000
	s_and_b32 s4, s40, 1
	v_lshl_add_u32 v162, s4, 14, v209
	s_bfe_u32 s100, s39, 0x1000a
	s_lshl_b32 s100, s100, 13
	s_lshl_b32 s4, s4, 15
	s_sub_i32 s18, s4, s100
	s_add_i32 s4, s4, s100
	v_add_u32_e32 v215, s4, v211
	v_add_u32_e32 v233, s18, v211
	v_add_u32_e32 v68, s1, v212
	v_add_u32_e32 v64, v68, v196
	v_add_u32_e32 v69, v68, v198
	ds_read_b64_tr_b16 v[234:235], v215 offset:0
	ds_read_b64_tr_b16 v[236:237], v215 offset:0x800
	ds_read_b128 v[64:67], v64
	ds_read_b128 v[118:121], v69
	v_add_u32_e32 v69, v68, v199
	v_add_u32_e32 v70, v68, v200
	ds_read_b128 v[122:125], v69
	ds_read_b128 v[126:129], v70
	ds_read_b64_tr_b16 v[238:239], v215 offset:0x1000
	ds_read_b64_tr_b16 v[240:241], v215 offset:0x1800
	v_add_u32_e32 v69, v68, v201
	v_add_u32_e32 v70, v68, v202
	ds_read_b128 v[134:137], v69
	ds_read_b128 v[138:141], v70
	v_add_u32_e32 v142, v68, v203
	v_add_u32_e32 v146, v68, v204
	s_cmp_gt_i32 s72, s87
	s_cselect_b32 s100, s21, s20
	v_sub_f32_e32 v160, s100, v158
	s_lshl_b32 s4, s72, 12
	s_add_u32 s4, s16, s4
	s_addc_u32 s5, s17, 0
	s_add_u32 s18, s4, 0x100
	s_addc_u32 s19, s5, 0
	s_and_b32 s100, s25, 0x8000
	s_add_i32 s100, s39, s100
	s_waitcnt lgkmcnt(8)
	v_mfma_f32_32x32x16_bf16 v[0:15], v[114:117], v[234:237], v[0:15]
	ds_read_b64_tr_b16 v[242:243], v233 offset:0x2000
	ds_read_b64_tr_b16 v[244:245], v233 offset:0x2800
	s_waitcnt lgkmcnt(9)
	v_mfma_f32_32x32x16_bf16 v[64:79], v[64:67], v[82:85], 0
	ds_read_b128 v[166:169], v162 offset:16
	ds_read_b128 v[162:165], v162
	s_waitcnt lgkmcnt(10)
	v_mfma_f32_32x32x16_bf16 v[64:79], v[118:121], v[86:89], v[64:79]
	ds_read_b128 v[142:145], v142
	ds_read_b128 v[146:149], v146
	s_waitcnt lgkmcnt(11)
	v_mfma_f32_32x32x16_bf16 v[64:79], v[122:125], v[90:93], v[64:79]
	ds_read_b64_tr_b16 v[246:247], v233 offset:0x3000
	ds_read_b64_tr_b16 v[248:249], v233 offset:0x3800
	s_waitcnt lgkmcnt(12)
	v_mfma_f32_32x32x16_bf16 v[64:79], v[126:129], v[94:97], v[64:79]
	ds_read_b64_tr_b16 v[126:127], v233 offset:0x3200
	ds_read_b64_tr_b16 v[128:129], v233 offset:0x3a00
	s_waitcnt lgkmcnt(12)
	v_mfma_f32_32x32x16_bf16 v[0:15], v[130:133], v[238:241], v[0:15]
	s_mov_b32 m0, s100
	s_waitcnt lgkmcnt(11)
	v_mfma_f32_32x32x16_bf16 v[64:79], v[134:137], v[98:101], v[64:79]
	global_load_lds_dwordx4 v152, s[4:5]
	ds_read_b64_tr_b16 v[134:135], v233 offset:0x2200
	ds_read_b64_tr_b16 v[136:137], v233 offset:0x2a00
	s_add_i32 m0, s100, 0x2000
	s_waitcnt lgkmcnt(12)
	v_mfma_f32_32x32x16_bf16 v[64:79], v[138:141], v[102:105], v[64:79]
	global_load_lds_dwordx4 v156, s[4:5]
	ds_read_b64_tr_b16 v[138:139], v215 offset:0x200
	ds_read_b64_tr_b16 v[140:141], v215 offset:0xa00
	s_add_i32 m0, s100, 0x4000
	s_waitcnt lgkmcnt(10)
	v_mfma_f32_32x32x16_bf16 v[0:15], v[162:165], v[242:245], v[0:15]
	global_load_lds_dwordx4 v152, s[18:19]
	s_add_i32 m0, s100, 0x6000
	s_waitcnt lgkmcnt(9)
	v_mfma_f32_32x32x16_bf16 v[64:79], v[142:145], v[106:109], v[64:79]
	ds_read_b64_tr_b16 v[142:143], v215 offset:0x1200
	ds_read_b64_tr_b16 v[144:145], v215 offset:0x1a00
	s_waitcnt lgkmcnt(10)
	v_mfma_f32_32x32x16_bf16 v[64:79], v[146:149], v[110:113], v[64:79]
	global_load_lds_dwordx4 v156, s[18:19]
	s_waitcnt lgkmcnt(8)
	v_mfma_f32_32x32x16_bf16 v[0:15], v[166:169], v[246:249], v[0:15]
	s_add_i32 s4, s40, 2
	s_cmp_ge_u32 s4, s11
	s_cbranch_scc1 .Lfast1_k_done
	s_lshl_b32 s4, s0, 12
	s_add_u32 s4, s14, s4
	s_addc_u32 s5, s15, 0
	s_add_u32 s4, s4, 0x100
	s_addc_u32 s5, s5, 0
	s_add_i32 s100, s38, s101
	s_mov_b32 m0, s100
	s_nop 0
	global_load_lds_dwordx4 v176, s[4:5]
	s_add_i32 m0, s100, 0x2000
	s_nop 0
	global_load_lds_dwordx4 v154, s[4:5]
